# GEMM K-loop back edge rotated: pointer advance, exit test and next-iteration scalar setup moved in front of the loop-back barrier
# baseline (speedup 1.0000x reference)
.Lk_body:
	s_waitcnt lgkmcnt(0)
	ds_read_b128 v[0:3], v96
	ds_read_b128 v[4:7], v96 offset:1024
	ds_read_b128 v[98:101], v96 offset:2048
	ds_read_b128 v[158:161], v96 offset:3072
	v_add_u32_e32 v96, s59, v162
	ds_read_b128 v[164:167], v96
	ds_read_b128 v[168:171], v96 offset:1024
	ds_read_b128 v[172:175], v96 offset:2048
	ds_read_b128 v[198:201], v96 offset:3072
	v_lshl_add_u64 v[102:103], s[28:29], 0, v[154:155]
	s_add_i32 m0, s75, 0xc000
	ds_read_b128 v[202:205], v163
	ds_read_b128 v[206:209], v163 offset:1024
	ds_read_b128 v[210:213], v163 offset:2048
	ds_read_b128 v[214:217], v163 offset:3072
	ds_read_b128 v[218:221], v163 offset:4096
	ds_read_b128 v[222:225], v163 offset:5120
	ds_read_b128 v[226:229], v163 offset:6144
	ds_read_b128 v[230:233], v163 offset:7168
	global_load_lds_dwordx4 v[102:103], off
	v_lshl_add_u64 v[102:103], s[28:29], 0, v[156:157]
	s_add_i32 m0, s75, 0xe000
	s_nop 0
	global_load_lds_dwordx4 v[102:103], off
	s_waitcnt vmcnt(8)
	s_waitcnt lgkmcnt(0)
	s_barrier
	s_waitcnt lgkmcnt(0)
	v_mfma_f32_16x16x32_bf16 v[140:143], v[0:3], v[202:205], v[140:143]
	v_mfma_f32_16x16x32_bf16 v[136:139], v[98:101], v[202:205], v[136:139]
	v_mfma_f32_16x16x32_bf16 v[132:135], v[0:3], v[210:213], v[132:135]
	v_mfma_f32_16x16x32_bf16 v[128:131], v[98:101], v[210:213], v[128:131]
	v_mfma_f32_16x16x32_bf16 v[124:127], v[0:3], v[218:221], v[124:127]
	v_mfma_f32_16x16x32_bf16 v[120:123], v[98:101], v[218:221], v[120:123]
	v_mfma_f32_16x16x32_bf16 v[116:119], v[0:3], v[226:229], v[116:119]
	v_mfma_f32_16x16x32_bf16 v[112:115], v[98:101], v[226:229], v[112:115]
	v_mfma_f32_16x16x32_bf16 v[140:143], v[4:7], v[206:209], v[140:143]
	v_mfma_f32_16x16x32_bf16 v[136:139], v[158:161], v[206:209], v[136:139]
	v_mfma_f32_16x16x32_bf16 v[132:135], v[4:7], v[214:217], v[132:135]
	v_mfma_f32_16x16x32_bf16 v[128:131], v[158:161], v[214:217], v[128:131]
	v_mfma_f32_16x16x32_bf16 v[124:127], v[4:7], v[222:225], v[124:127]
	v_mfma_f32_16x16x32_bf16 v[120:123], v[158:161], v[222:225], v[120:123]
	v_mfma_f32_16x16x32_bf16 v[116:119], v[4:7], v[230:233], v[116:119]
	v_mfma_f32_16x16x32_bf16 v[112:115], v[158:161], v[230:233], v[112:115]
	v_mfma_f32_16x16x32_bf16 v[68:71], v[164:167], v[202:205], v[68:71]
	v_mfma_f32_16x16x32_bf16 v[64:67], v[172:175], v[202:205], v[64:67]
	v_mfma_f32_16x16x32_bf16 v[60:63], v[164:167], v[210:213], v[60:63]
	v_mfma_f32_16x16x32_bf16 v[56:59], v[172:175], v[210:213], v[56:59]
	v_mfma_f32_16x16x32_bf16 v[52:55], v[164:167], v[218:221], v[52:55]
	v_mfma_f32_16x16x32_bf16 v[48:51], v[172:175], v[218:221], v[48:51]
	v_mfma_f32_16x16x32_bf16 v[44:47], v[164:167], v[226:229], v[44:47]
	v_mfma_f32_16x16x32_bf16 v[40:43], v[172:175], v[226:229], v[40:43]
	v_mfma_f32_16x16x32_bf16 v[68:71], v[168:171], v[206:209], v[68:71]
	v_mfma_f32_16x16x32_bf16 v[64:67], v[198:201], v[206:209], v[64:67]
	v_mfma_f32_16x16x32_bf16 v[60:63], v[168:171], v[214:217], v[60:63]
	v_mfma_f32_16x16x32_bf16 v[56:59], v[198:201], v[214:217], v[56:59]
	v_mfma_f32_16x16x32_bf16 v[52:55], v[168:171], v[222:225], v[52:55]
	v_mfma_f32_16x16x32_bf16 v[48:51], v[198:201], v[222:225], v[48:51]
	v_mfma_f32_16x16x32_bf16 v[44:47], v[168:171], v[230:233], v[44:47]
	v_mfma_f32_16x16x32_bf16 v[40:43], v[198:201], v[230:233], v[40:43]
	s_barrier
	s_add_i32 s80, s80, s74
	v_lshl_add_u64 v[176:177], s[78:79], 0, v[146:147]
	s_mov_b32 m0, s80
	ds_read_b128 v[202:205], v163 offset:16384
	ds_read_b128 v[206:209], v163 offset:17408
	ds_read_b128 v[210:213], v163 offset:18432
	ds_read_b128 v[214:217], v163 offset:19456
	ds_read_b128 v[218:221], v163 offset:20480
	ds_read_b128 v[222:225], v163 offset:21504
	ds_read_b128 v[226:229], v163 offset:22528
	ds_read_b128 v[230:233], v163 offset:23552
	global_load_lds_dwordx4 v[176:177], off
	s_add_i32 m0, s80, 0x2000
	v_lshl_add_u64 v[186:187], s[78:79], 0, v[150:151]
	s_add_u32 s78, s78, s4
	s_addc_u32 s79, s79, 0
	s_add_i32 s59, s59, s74
	global_load_lds_dwordx4 v[186:187], off
	v_lshl_add_u64 v[234:235], s[78:79], 0, v[146:147]
	s_mov_b32 m0, s59
	v_lshl_add_u64 v[236:237], s[78:79], 0, v[150:151]
	global_load_lds_dwordx4 v[234:235], off
	s_add_i32 m0, s59, 0x2000
	v_lshl_add_u64 v[238:239], s[26:27], 0, v[144:145]
	global_load_lds_dwordx4 v[236:237], off
	s_mov_b32 m0, s75
	v_lshl_add_u64 v[240:241], s[26:27], 0, v[148:149]
	global_load_lds_dwordx4 v[238:239], off
	s_mov_b32 m0, s3
	s_nop 0
	global_load_lds_dwordx4 v[240:241], off
	s_waitcnt vmcnt(8)
	s_waitcnt lgkmcnt(0)
	s_barrier
	s_waitcnt lgkmcnt(0)
	v_mfma_f32_16x16x32_bf16 v[108:111], v[0:3], v[202:205], v[108:111]
	v_mfma_f32_16x16x32_bf16 v[102:105], v[98:101], v[202:205], v[104:107]
	v_mfma_f32_16x16x32_bf16 v[92:95], v[0:3], v[210:213], v[92:95]
	v_mfma_f32_16x16x32_bf16 v[88:91], v[98:101], v[210:213], v[88:91]
	v_mfma_f32_16x16x32_bf16 v[84:87], v[0:3], v[218:221], v[84:87]
	v_mfma_f32_16x16x32_bf16 v[80:83], v[98:101], v[218:221], v[80:83]
	v_mfma_f32_16x16x32_bf16 v[0:3], v[0:3], v[226:229], v[76:79]
	v_mfma_f32_16x16x32_bf16 v[108:111], v[4:7], v[206:209], v[108:111]
	v_mfma_f32_16x16x32_bf16 v[102:105], v[158:161], v[206:209], v[102:105]
	v_mfma_f32_16x16x32_bf16 v[92:95], v[4:7], v[214:217], v[92:95]
	v_mfma_f32_16x16x32_bf16 v[88:91], v[158:161], v[214:217], v[88:91]
	v_mfma_f32_16x16x32_bf16 v[84:87], v[4:7], v[222:225], v[84:87]
	v_mfma_f32_16x16x32_bf16 v[80:83], v[158:161], v[222:225], v[80:83]
	v_mfma_f32_16x16x32_bf16 v[0:3], v[4:7], v[230:233], v[0:3]
	v_mfma_f32_16x16x32_bf16 v[4:7], v[98:101], v[226:229], v[72:75]
	v_mfma_f32_16x16x32_bf16 v[4:7], v[158:161], v[230:233], v[4:7]
	v_mfma_f32_16x16x32_bf16 v[36:39], v[164:167], v[202:205], v[36:39]
	v_mfma_f32_16x16x32_bf16 v[32:35], v[172:175], v[202:205], v[32:35]
	v_mfma_f32_16x16x32_bf16 v[28:31], v[164:167], v[210:213], v[28:31]
	v_mfma_f32_16x16x32_bf16 v[24:27], v[172:175], v[210:213], v[24:27]
	v_mfma_f32_16x16x32_bf16 v[20:23], v[164:167], v[218:221], v[20:23]
	v_mfma_f32_16x16x32_bf16 v[16:19], v[172:175], v[218:221], v[16:19]
	v_mfma_f32_16x16x32_bf16 v[12:15], v[164:167], v[226:229], v[12:15]
	v_mfma_f32_16x16x32_bf16 v[8:11], v[172:175], v[226:229], v[8:11]
	v_mfma_f32_16x16x32_bf16 v[36:39], v[168:171], v[206:209], v[36:39]
	v_mfma_f32_16x16x32_bf16 v[32:35], v[198:201], v[206:209], v[32:35]
	v_mfma_f32_16x16x32_bf16 v[28:31], v[168:171], v[214:217], v[28:31]
	v_mfma_f32_16x16x32_bf16 v[24:27], v[198:201], v[214:217], v[24:27]
	v_mfma_f32_16x16x32_bf16 v[20:23], v[168:171], v[222:225], v[20:23]
	v_mfma_f32_16x16x32_bf16 v[16:19], v[198:201], v[222:225], v[16:19]
	v_mfma_f32_16x16x32_bf16 v[12:15], v[168:171], v[230:233], v[12:15]
	v_mfma_f32_16x16x32_bf16 v[8:11], v[198:201], v[230:233], v[8:11]
	s_barrier
	s_add_i32 s59, 0, 0x18000
	v_add_u32_e32 v96, s59, v162
	s_add_i32 s78, 0, 0x1c000
	ds_read_b128 v[72:75], v96
	ds_read_b128 v[76:79], v96 offset:1024
	ds_read_b128 v[98:101], v96 offset:2048
	ds_read_b128 v[158:161], v96 offset:3072
	v_add_u32_e32 v96, s78, v162
	ds_read_b128 v[164:167], v96
	ds_read_b128 v[168:171], v96 offset:1024
	ds_read_b128 v[172:175], v96 offset:2048
	ds_read_b128 v[198:201], v96 offset:3072
	s_add_u32 s26, s26, s4
	s_addc_u32 s27, s27, 0
	s_mov_b32 m0, s23
	v_lshl_add_u64 v[106:107], s[26:27], 0, v[144:145]
	ds_read_b128 v[202:205], v163 offset:32768
	ds_read_b128 v[206:209], v163 offset:33792
	ds_read_b128 v[210:213], v163 offset:34816
	ds_read_b128 v[214:217], v163 offset:35840
	ds_read_b128 v[218:221], v163 offset:36864
	ds_read_b128 v[222:225], v163 offset:37888
	ds_read_b128 v[226:229], v163 offset:38912
	ds_read_b128 v[230:233], v163 offset:39936
	global_load_lds_dwordx4 v[106:107], off
	v_lshl_add_u64 v[106:107], s[26:27], 0, v[148:149]
	s_mov_b32 m0, s72
	s_nop 0
	global_load_lds_dwordx4 v[106:107], off
	s_waitcnt vmcnt(8)
	s_waitcnt lgkmcnt(0)
	s_barrier
	s_waitcnt lgkmcnt(0)
	v_mfma_f32_16x16x32_bf16 v[140:143], v[72:75], v[202:205], v[140:143]
	v_mfma_f32_16x16x32_bf16 v[136:139], v[98:101], v[202:205], v[136:139]
	v_mfma_f32_16x16x32_bf16 v[132:135], v[72:75], v[210:213], v[132:135]
	v_mfma_f32_16x16x32_bf16 v[128:131], v[98:101], v[210:213], v[128:131]
	v_mfma_f32_16x16x32_bf16 v[124:127], v[72:75], v[218:221], v[124:127]
	v_mfma_f32_16x16x32_bf16 v[120:123], v[98:101], v[218:221], v[120:123]
	v_mfma_f32_16x16x32_bf16 v[116:119], v[72:75], v[226:229], v[116:119]
	v_mfma_f32_16x16x32_bf16 v[112:115], v[98:101], v[226:229], v[112:115]
	v_mfma_f32_16x16x32_bf16 v[140:143], v[76:79], v[206:209], v[140:143]
	v_mfma_f32_16x16x32_bf16 v[136:139], v[158:161], v[206:209], v[136:139]
	v_mfma_f32_16x16x32_bf16 v[132:135], v[76:79], v[214:217], v[132:135]
	v_mfma_f32_16x16x32_bf16 v[128:131], v[158:161], v[214:217], v[128:131]
	v_mfma_f32_16x16x32_bf16 v[124:127], v[76:79], v[222:225], v[124:127]
	v_mfma_f32_16x16x32_bf16 v[120:123], v[158:161], v[222:225], v[120:123]
	v_mfma_f32_16x16x32_bf16 v[116:119], v[76:79], v[230:233], v[116:119]
	v_mfma_f32_16x16x32_bf16 v[112:115], v[158:161], v[230:233], v[112:115]
	v_mfma_f32_16x16x32_bf16 v[68:71], v[164:167], v[202:205], v[68:71]
	v_mfma_f32_16x16x32_bf16 v[64:67], v[172:175], v[202:205], v[64:67]
	v_mfma_f32_16x16x32_bf16 v[60:63], v[164:167], v[210:213], v[60:63]
	v_mfma_f32_16x16x32_bf16 v[56:59], v[172:175], v[210:213], v[56:59]
	v_mfma_f32_16x16x32_bf16 v[52:55], v[164:167], v[218:221], v[52:55]
	v_mfma_f32_16x16x32_bf16 v[48:51], v[172:175], v[218:221], v[48:51]
	v_mfma_f32_16x16x32_bf16 v[44:47], v[164:167], v[226:229], v[44:47]
	v_mfma_f32_16x16x32_bf16 v[40:43], v[172:175], v[226:229], v[40:43]
	v_mfma_f32_16x16x32_bf16 v[68:71], v[168:171], v[206:209], v[68:71]
	v_mfma_f32_16x16x32_bf16 v[64:67], v[198:201], v[206:209], v[64:67]
	v_mfma_f32_16x16x32_bf16 v[60:63], v[168:171], v[214:217], v[60:63]
	v_mfma_f32_16x16x32_bf16 v[56:59], v[198:201], v[214:217], v[56:59]
	v_mfma_f32_16x16x32_bf16 v[52:55], v[168:171], v[222:225], v[52:55]
	v_mfma_f32_16x16x32_bf16 v[48:51], v[198:201], v[222:225], v[48:51]
	v_mfma_f32_16x16x32_bf16 v[44:47], v[168:171], v[230:233], v[44:47]
	v_mfma_f32_16x16x32_bf16 v[40:43], v[198:201], v[230:233], v[40:43]
	s_barrier
	s_add_i32 s26, s59, s74
	v_lshl_add_u64 v[106:107], v[176:177], 0, s[20:21]
	s_mov_b32 m0, s26
	ds_read_b128 v[202:205], v163 offset:49152
	ds_read_b128 v[206:209], v163 offset:50176
	ds_read_b128 v[210:213], v163 offset:51200
	ds_read_b128 v[214:217], v163 offset:52224
	ds_read_b128 v[218:221], v163 offset:53248
	ds_read_b128 v[222:225], v163 offset:54272
	ds_read_b128 v[226:229], v163 offset:55296
	ds_read_b128 v[230:233], v163 offset:56320
	global_load_lds_dwordx4 v[106:107], off
	v_lshl_add_u64 v[106:107], v[186:187], 0, s[20:21]
	s_add_i32 m0, s26, 0x2000
	s_add_i32 s26, s78, s74
	global_load_lds_dwordx4 v[106:107], off
	v_lshl_add_u64 v[106:107], v[234:235], 0, s[20:21]
	s_mov_b32 m0, s26
	s_nop 0
	global_load_lds_dwordx4 v[106:107], off
	v_lshl_add_u64 v[106:107], v[236:237], 0, s[20:21]
	s_add_i32 m0, s26, 0x2000
	s_nop 0
	global_load_lds_dwordx4 v[106:107], off
	v_lshl_add_u64 v[106:107], v[238:239], 0, s[20:21]
	s_mov_b32 m0, s60
	s_nop 0
	global_load_lds_dwordx4 v[106:107], off
	v_lshl_add_u64 v[106:107], v[240:241], 0, s[20:21]
	s_mov_b32 m0, s61
	s_nop 0
	global_load_lds_dwordx4 v[106:107], off
	s_waitcnt vmcnt(8)
	s_waitcnt lgkmcnt(0)
	s_barrier
	s_waitcnt lgkmcnt(0)
	v_mfma_f32_16x16x32_bf16 v[106:109], v[72:75], v[202:205], v[108:111]
	v_mfma_f32_16x16x32_bf16 v[92:95], v[72:75], v[210:213], v[92:95]
	v_mfma_f32_16x16x32_bf16 v[84:87], v[72:75], v[218:221], v[84:87]
	v_mfma_f32_16x16x32_bf16 v[0:3], v[72:75], v[226:229], v[0:3]
	v_mfma_f32_16x16x32_bf16 v[108:111], v[76:79], v[206:209], v[106:109]
	v_mfma_f32_16x16x32_bf16 v[102:105], v[98:101], v[202:205], v[102:105]
	v_mfma_f32_16x16x32_bf16 v[92:95], v[76:79], v[214:217], v[92:95]
	v_mfma_f32_16x16x32_bf16 v[88:91], v[98:101], v[210:213], v[88:91]
	v_mfma_f32_16x16x32_bf16 v[84:87], v[76:79], v[222:225], v[84:87]
	v_mfma_f32_16x16x32_bf16 v[80:83], v[98:101], v[218:221], v[80:83]
	v_mfma_f32_16x16x32_bf16 v[76:79], v[76:79], v[230:233], v[0:3]
	v_mfma_f32_16x16x32_bf16 v[0:3], v[98:101], v[226:229], v[4:7]
	v_mfma_f32_16x16x32_bf16 v[104:107], v[158:161], v[206:209], v[102:105]
	v_mfma_f32_16x16x32_bf16 v[88:91], v[158:161], v[214:217], v[88:91]
	v_mfma_f32_16x16x32_bf16 v[80:83], v[158:161], v[222:225], v[80:83]
	v_mfma_f32_16x16x32_bf16 v[72:75], v[158:161], v[230:233], v[0:3]
	v_mfma_f32_16x16x32_bf16 v[0:3], v[164:167], v[202:205], v[36:39]
	v_mfma_f32_16x16x32_bf16 v[36:39], v[168:171], v[206:209], v[0:3]
	v_mfma_f32_16x16x32_bf16 v[0:3], v[172:175], v[202:205], v[32:35]
	v_mfma_f32_16x16x32_bf16 v[32:35], v[198:201], v[206:209], v[0:3]
	v_mfma_f32_16x16x32_bf16 v[0:3], v[164:167], v[210:213], v[28:31]
	v_mfma_f32_16x16x32_bf16 v[28:31], v[168:171], v[214:217], v[0:3]
	v_mfma_f32_16x16x32_bf16 v[0:3], v[172:175], v[210:213], v[24:27]
	v_mfma_f32_16x16x32_bf16 v[24:27], v[198:201], v[214:217], v[0:3]
	v_mfma_f32_16x16x32_bf16 v[0:3], v[164:167], v[218:221], v[20:23]
	v_mfma_f32_16x16x32_bf16 v[20:23], v[168:171], v[222:225], v[0:3]
	v_mfma_f32_16x16x32_bf16 v[0:3], v[172:175], v[218:221], v[16:19]
	v_mfma_f32_16x16x32_bf16 v[16:19], v[198:201], v[222:225], v[0:3]
	v_mfma_f32_16x16x32_bf16 v[0:3], v[164:167], v[226:229], v[12:15]
	v_mfma_f32_16x16x32_bf16 v[12:15], v[168:171], v[230:233], v[0:3]
	v_mfma_f32_16x16x32_bf16 v[0:3], v[172:175], v[226:229], v[8:11]
	v_mfma_f32_16x16x32_bf16 v[8:11], v[198:201], v[230:233], v[0:3]
	s_add_u32 s28, s28, 0x100
	s_addc_u32 s29, s29, 0
	s_add_u32 s41, s41, 0x100
	s_addc_u32 s54, s54, 0
	s_cmp_ge_u32 s55, s73
	s_mov_b32 s26, s55
	s_cbranch_scc1 .Lk_exit
	s_add_i32 s55, s26, 2
	s_add_u32 s59, s28, 0x80
	s_addc_u32 s27, s29, 0
	s_add_i32 s80, 0, 0x10000
	s_cmp_eq_u32 s62, s26
	s_cselect_b32 s27, s1, s27
	s_cselect_b32 s26, s0, s59
	v_add_u32_e32 v96, s80, v162
	s_cselect_b32 s79, s77, s54
	s_cselect_b32 s78, s76, s41
	s_add_i32 s59, 0, 0x14000
	s_barrier
	s_branch .Lk_body
.Lk_exit:
	s_barrier
	s_and_b64 vcc, exec, s[18:19]
	s_cbranch_vccz .LBB0_360
	s_barrier
